# v11 + RG-LRU item numbering: a workgroup's four waves take adjacent channel groups of one batch (P6 and P7)
# baseline (speedup 1.0000x reference)
.LBB0_979:
	s_cmp_lg_u32 0, -1
	s_cselect_b32 s8, 0, 0
	s_add_i32 s8, s8, 0xc000
	v_add_u32_e32 v32, s8, v132
	v_add3_u32 v33, v32, v137, v138
	v_add_f32_e32 v32, v80, v81
	v_add_f32_e32 v32, v82, v32
	v_add_f32_e32 v32, v83, v32
	v_add_f32_e32 v32, v84, v32
	v_add_f32_e32 v32, v85, v32
	v_add_f32_e32 v32, v86, v32
	v_add_f32_e32 v32, v87, v32
	v_add_f32_e32 v32, v88, v32
	v_add_f32_e32 v32, v89, v32
	v_add_f32_e32 v32, v90, v32
	v_add_f32_e32 v32, v91, v32
	v_add_f32_e32 v32, v92, v32
	v_add_f32_e32 v32, v93, v32
	v_add_f32_e32 v32, v94, v32
	v_add_f32_e32 v32, v95, v32
	v_add_f32_e32 v32, v32, v48
	v_add_f32_e32 v32, v49, v32
	v_add_f32_e32 v32, v50, v32
	v_add_f32_e32 v32, v51, v32
	v_add_f32_e32 v32, v52, v32
	v_add_f32_e32 v32, v53, v32
	v_add_f32_e32 v32, v54, v32
	v_add_f32_e32 v32, v55, v32
	v_add_f32_e32 v32, v56, v32
	v_add_f32_e32 v32, v57, v32
	v_add_f32_e32 v32, v58, v32
	v_add_f32_e32 v32, v59, v32
	v_add_f32_e32 v32, v60, v32
	v_add_f32_e32 v32, v61, v32
	v_add_f32_e32 v32, v62, v32
	v_add_f32_e32 v32, v63, v32
	v_add_f32_e32 v32, v40, v32
	v_cvt_pk_bf16_f32 v34, v80, v81
	v_cvt_pk_bf16_f32 v35, v82, v83
	v_cvt_pk_bf16_f32 v36, v84, v85
	v_cvt_pk_bf16_f32 v37, v86, v87
	v_cvt_pk_bf16_f32 v38, v88, v89
	v_cvt_pk_bf16_f32 v39, v90, v91
	v_cvt_pk_bf16_f32 v40, v92, v93
	v_cvt_pk_bf16_f32 v41, v94, v95
	v_cvt_pk_bf16_f32 v42, v48, v49
	v_cvt_pk_bf16_f32 v43, v50, v51
	v_cvt_pk_bf16_f32 v44, v52, v53
	v_cvt_pk_bf16_f32 v45, v54, v55
	v_cvt_pk_bf16_f32 v46, v56, v57
	v_cvt_pk_bf16_f32 v47, v58, v59
	v_cvt_pk_bf16_f32 v48, v60, v61
	v_cvt_pk_bf16_f32 v49, v62, v63
	ds_read_b64_tr_b16 v[50:51],v33 offset:0
	ds_read_b64_tr_b16 v[52:53],v33 offset:512
	ds_read_b64_tr_b16 v[54:55],v33 offset:1024
	ds_read_b64_tr_b16 v[56:57],v33 offset:1536
	ds_read_b64_tr_b16 v[58:59],v33 offset:2048
	ds_read_b64_tr_b16 v[60:61],v33 offset:2560
	ds_read_b64_tr_b16 v[62:63],v33 offset:3072
	ds_read_b64_tr_b16 v[64:65],v33 offset:3584
	s_waitcnt lgkmcnt(0)
	s_nop 0
	v_mfma_f32_32x32x16_bf16 v[0:15], v[34:37], v[50:53], v[0:15]
	ds_read_b64_tr_b16 v[50:51],v33 offset:4096
	ds_read_b64_tr_b16 v[52:53],v33 offset:4608
	v_mfma_f32_32x32x16_bf16 v[0:15], v[38:41], v[54:57], v[0:15]
	ds_read_b64_tr_b16 v[54:55],v33 offset:5120
	ds_read_b64_tr_b16 v[56:57],v33 offset:5632
	v_mfma_f32_32x32x16_bf16 v[0:15], v[42:45], v[58:61], v[0:15]
	ds_read_b64_tr_b16 v[58:59],v33 offset:6144
	ds_read_b64_tr_b16 v[60:61],v33 offset:6656
	ds_read_b64_tr_b16 v[66:67],v33 offset:7168
	ds_read_b64_tr_b16 v[68:69],v33 offset:7680
	s_waitcnt lgkmcnt(0)
	v_mfma_f32_32x32x16_bf16 v[0:15], v[46:49], v[62:65], v[0:15]
	v_mfma_f32_32x32x16_bf16 v[16:31], v[34:37], v[50:53], v[16:31]
	v_mov_b32_e32 v33, v32
	s_nop 1
	v_permlane32_swap_b32_e32 v32, v33
	v_mfma_f32_32x32x16_bf16 v[16:31], v[38:41], v[54:57], v[16:31]
	v_mfma_f32_32x32x16_bf16 v[16:31], v[42:45], v[58:61], v[16:31]
	v_mfma_f32_32x32x16_bf16 v[16:31], v[46:49], v[66:69], v[16:31]
	s_and_saveexec_b64 s[8:9], s[0:1]
	v_add_f32_e32 v32, v32, v33
	v_lshl_add_u32 v33, v184, 2, s15
	ds_write_b32 v33, v32 offset:128
	s_or_b64 exec, exec, s[8:9]
	s_add_u32 s38, s4, 0x3800000
	s_addc_u32 s39, s5, 0
	s_add_u32 s28, s4, 0x700000
	s_addc_u32 s29, s5, 0
	s_waitcnt lgkmcnt(0)
	s_add_u32 s30, s4, 0xf9ff000
	ds_read_b128 v[32:35], v140 offset:128
	ds_read_b128 v[36:39], v140 offset:160
	s_addc_u32 s31, s5, 0
	s_add_u32 s20, s4, 0xf800000
	s_addc_u32 s21, s5, 0
	s_lshl_b64 s[0:1], s[6:7], 24
	s_add_u32 s0, s4, s0
	s_addc_u32 s1, s5, s1
	s_waitcnt lgkmcnt(1)
	v_rcp_f32_e32 v40, v32
	s_add_u32 s4, s0, s14
	s_addc_u32 s1, s1, 0
	s_lshl_b32 s0, s90, 12
	s_add_i32 s0, s0, 0
	v_rcp_f32_e32 v41, v33
	s_add_i32 s0, s0, 0x12800
	v_lshlrev_b32_e32 v48, 9, v136
	v_lshlrev_b32_e32 v49, 1, v135
	v_mul_f32_e32 v0, v0, v40
	v_add3_u32 v48, s0, v48, v49
	v_cvt_pk_bf16_f32 v0, v0, s0
	ds_write_b16 v48, v0
	v_mul_f32_e32 v0, v16, v40
	v_cvt_pk_bf16_f32 v0, v0, s0
	v_rcp_f32_e32 v42, v34
	ds_write_b16 v48, v0 offset:64
	v_mul_f32_e32 v0, v1, v41
	v_cvt_pk_bf16_f32 v0, v0, s0
	ds_write_b16 v48, v0 offset:128
	v_mul_f32_e32 v0, v17, v41
	v_cvt_pk_bf16_f32 v0, v0, s0
	v_rcp_f32_e32 v43, v35
	ds_write_b16 v48, v0 offset:192
	v_mul_f32_e32 v0, v2, v42
	v_cvt_pk_bf16_f32 v0, v0, s0
	ds_write_b16 v48, v0 offset:256
	v_mul_f32_e32 v0, v18, v42
	v_cvt_pk_bf16_f32 v0, v0, s0
	s_waitcnt lgkmcnt(5)
	v_rcp_f32_e32 v44, v36
	ds_write_b16 v48, v0 offset:320
	v_mul_f32_e32 v0, v3, v43
	v_cvt_pk_bf16_f32 v0, v0, s0
	ds_write_b16 v48, v0 offset:384
	v_mul_f32_e32 v0, v19, v43
	v_cvt_pk_bf16_f32 v0, v0, s0
	v_rcp_f32_e32 v45, v37
	ds_write_b16 v48, v0 offset:448
	v_mul_f32_e32 v0, v4, v44
	v_cvt_pk_bf16_f32 v0, v0, s0
	ds_write_b16 v48, v0 offset:1024
	v_mul_f32_e32 v0, v20, v44
	v_cvt_pk_bf16_f32 v0, v0, s0
	v_rcp_f32_e32 v46, v38
	ds_write_b16 v48, v0 offset:1088
	v_mul_f32_e32 v0, v5, v45
	v_cvt_pk_bf16_f32 v0, v0, s0
	ds_write_b16 v48, v0 offset:1152
	v_mul_f32_e32 v0, v21, v45
	ds_read_b128 v[32:35], v140 offset:192
	v_cvt_pk_bf16_f32 v0, v0, s0
	v_rcp_f32_e32 v47, v39
	ds_write_b16 v48, v0 offset:1216
	v_mul_f32_e32 v0, v6, v46
	v_cvt_pk_bf16_f32 v0, v0, s0
	ds_write_b16 v48, v0 offset:1280
	v_mul_f32_e32 v0, v22, v46
	v_cvt_pk_bf16_f32 v0, v0, s0
	ds_read_b128 v[36:39], v140 offset:224
	s_waitcnt lgkmcnt(3)
	v_rcp_f32_e32 v32, v32
	ds_write_b16 v48, v0 offset:1344
	v_mul_f32_e32 v0, v7, v47
	v_cvt_pk_bf16_f32 v0, v0, s0
	ds_write_b16 v48, v0 offset:1408
	v_mul_f32_e32 v0, v23, v47
	v_cvt_pk_bf16_f32 v0, v0, s0
	v_rcp_f32_e32 v33, v33
	ds_write_b16 v48, v0 offset:1472
	v_mul_f32_e32 v0, v8, v32
	v_cvt_pk_bf16_f32 v0, v0, s0
	ds_write_b16 v48, v0 offset:2048
	v_mul_f32_e32 v0, v24, v32
	v_cvt_pk_bf16_f32 v0, v0, s0
	v_rcp_f32_e32 v34, v34
	ds_write_b16 v48, v0 offset:2112
	v_mul_f32_e32 v0, v9, v33
	v_cvt_pk_bf16_f32 v0, v0, s0
	ds_write_b16 v48, v0 offset:2176
	v_mul_f32_e32 v0, v25, v33
	v_cvt_pk_bf16_f32 v0, v0, s0
	v_rcp_f32_e32 v35, v35
	ds_write_b16 v48, v0 offset:2240
	v_mul_f32_e32 v0, v10, v34
	v_cvt_pk_bf16_f32 v0, v0, s0
	ds_write_b16 v48, v0 offset:2304
	v_mul_f32_e32 v0, v26, v34
	v_cvt_pk_bf16_f32 v0, v0, s0
	s_waitcnt lgkmcnt(8)
	v_rcp_f32_e32 v36, v36
	ds_write_b16 v48, v0 offset:2368
	v_mul_f32_e32 v0, v11, v35
	v_cvt_pk_bf16_f32 v0, v0, s0
	ds_write_b16 v48, v0 offset:2432
	v_mul_f32_e32 v0, v27, v35
	v_cvt_pk_bf16_f32 v0, v0, s0
	v_rcp_f32_e32 v37, v37
	ds_write_b16 v48, v0 offset:2496
	v_mul_f32_e32 v0, v12, v36
	v_cvt_pk_bf16_f32 v0, v0, s0
	ds_write_b16 v48, v0 offset:3072
	v_mul_f32_e32 v0, v28, v36
	v_cvt_pk_bf16_f32 v0, v0, s0
	v_rcp_f32_e32 v38, v38
	ds_write_b16 v48, v0 offset:3136
	v_mul_f32_e32 v0, v13, v37
	v_cvt_pk_bf16_f32 v0, v0, s0
	ds_write_b16 v48, v0 offset:3200
	v_mul_f32_e32 v0, v29, v37
	v_cvt_pk_bf16_f32 v0, v0, s0
	v_rcp_f32_e32 v39, v39
	ds_write_b16 v48, v0 offset:3264
	v_mul_f32_e32 v0, v14, v38
	v_cvt_pk_bf16_f32 v0, v0, s0
	ds_write_b16 v48, v0 offset:3328
	v_mul_f32_e32 v0, v30, v38
	v_cvt_pk_bf16_f32 v0, v0, s0
	ds_write_b16 v48, v0 offset:3392
	v_mul_f32_e32 v0, v15, v39
	v_cvt_pk_bf16_f32 v0, v0, s0
	ds_write_b16 v48, v0 offset:3456
	v_mul_f32_e32 v0, v31, v39
	v_cvt_pk_bf16_f32 v0, v0, s0
	s_lshl_b64 s[2:3], s[2:3], 11
	ds_write_b16 v48, v0 offset:3520
	s_add_u32 s2, s4, s2
	v_and_b32_e32 v0, 56, v134
	s_addc_u32 s3, s1, s3
	v_ashrrev_i32_e32 v116, 3, v184
	v_lshlrev_b32_e32 v124, 1, v0
	v_mov_b32_e32 v125, 0
	v_lshl_add_u64 v[16:17], s[2:3], 0, v[124:125]
	s_mov_b64 s[2:3], 0xb000600
	v_ashrrev_i32_e32 v117, 31, v116
	v_lshl_add_u64 v[18:19], v[16:17], 0, s[2:3]
	v_lshlrev_b64 v[20:21], 11, v[116:117]
	s_waitcnt lgkmcnt(0)
	v_lshl_add_u64 v[0:1], v[18:19], 0, v[20:21]
	global_load_dwordx4 v[0:3], v[0:1], off
	v_add_u32_e32 v22, 8, v116
	v_ashrrev_i32_e32 v23, 31, v22
	v_lshlrev_b64 v[24:25], 11, v[22:23]
	v_lshl_add_u64 v[4:5], v[18:19], 0, v[24:25]
	global_load_dwordx4 v[4:7], v[4:5], off
	v_add_u32_e32 v26, 16, v116
	v_ashrrev_i32_e32 v27, 31, v26
	v_lshlrev_b64 v[28:29], 11, v[26:27]
	v_lshl_add_u64 v[8:9], v[18:19], 0, v[28:29]
	v_add_u32_e32 v27, s0, v124
	global_load_dwordx4 v[8:11], v[8:9], off
	v_lshl_add_u32 v12, v116, 7, v27
	ds_read_b128 v[12:15], v12
	s_mov_b64 s[0:1], 0xd800600
	v_lshl_add_u64 v[30:31], v[16:17], 0, s[0:1]
	v_lshl_add_u64 v[20:21], v[30:31], 0, v[20:21]
	s_add_i32 s33, s70, 0
	s_waitcnt lgkmcnt(0)
	v_lshlrev_b32_e32 v16, 16, v12
	v_and_b32_e32 v17, 0xffff0000, v12
	v_lshlrev_b32_e32 v12, 16, v13
	v_and_b32_e32 v13, 0xffff0000, v13
	s_cmpk_gt_u32 s91, 0xff
	s_waitcnt vmcnt(2)
	v_lshlrev_b32_e32 v32, 16, v0
	v_and_b32_e32 v33, 0xffff0000, v0
	v_pk_mul_f32 v[16:17], v[16:17], v[32:33]
	v_add_u32_e32 v32, 24, v116
	v_ashrrev_i32_e32 v33, 31, v32
	v_lshlrev_b64 v[34:35], 11, v[32:33]
	v_cvt_pk_bf16_f32 v0, v16, v17
	v_lshl_add_u64 v[16:17], v[18:19], 0, v[34:35]
	global_load_dwordx4 v[16:19], v[16:17], off
	v_lshlrev_b32_e32 v36, 16, v1
	v_and_b32_e32 v37, 0xffff0000, v1
	v_pk_mul_f32 v[12:13], v[12:13], v[36:37]
	v_lshlrev_b32_e32 v36, 16, v2
	v_cvt_pk_bf16_f32 v1, v12, v13
	v_lshlrev_b32_e32 v12, 16, v14
	v_and_b32_e32 v13, 0xffff0000, v14
	v_and_b32_e32 v37, 0xffff0000, v2
	v_pk_mul_f32 v[12:13], v[12:13], v[36:37]
	v_lshlrev_b32_e32 v38, 16, v3
	v_and_b32_e32 v39, 0xffff0000, v3
	v_lshl_add_u32 v3, v22, 7, v27
	v_cvt_pk_bf16_f32 v2, v12, v13
	v_lshlrev_b32_e32 v36, 16, v15
	v_and_b32_e32 v37, 0xffff0000, v15
	ds_read_b128 v[12:15], v3
	v_pk_mul_f32 v[22:23], v[36:37], v[38:39]
	s_nop 0
	v_cvt_pk_bf16_f32 v3, v22, v23
	global_store_dwordx4 v[20:21], v[0:3], off sc1
	s_waitcnt lgkmcnt(0)
	s_nop 0
	v_lshlrev_b32_e32 v0, 16, v12
	v_and_b32_e32 v1, 0xffff0000, v12
	s_waitcnt vmcnt(3)
	v_lshlrev_b32_e32 v2, 16, v4
	v_and_b32_e32 v3, 0xffff0000, v4
	v_pk_mul_f32 v[0:1], v[0:1], v[2:3]
	v_lshlrev_b32_e32 v2, 16, v13
	v_and_b32_e32 v3, 0xffff0000, v13
	v_lshlrev_b32_e32 v4, 16, v5
	v_and_b32_e32 v5, 0xffff0000, v5
	v_pk_mul_f32 v[2:3], v[2:3], v[4:5]
	v_cvt_pk_bf16_f32 v0, v0, v1
	v_cvt_pk_bf16_f32 v1, v2, v3
	v_lshlrev_b32_e32 v2, 16, v14
	v_and_b32_e32 v3, 0xffff0000, v14
	v_lshlrev_b32_e32 v4, 16, v6
	v_and_b32_e32 v5, 0xffff0000, v6
	v_pk_mul_f32 v[2:3], v[2:3], v[4:5]
	v_lshlrev_b32_e32 v12, 16, v15
	v_cvt_pk_bf16_f32 v2, v2, v3
	v_lshl_add_u32 v3, v26, 7, v27
	v_and_b32_e32 v13, 0xffff0000, v15
	v_lshlrev_b32_e32 v14, 16, v7
	v_and_b32_e32 v15, 0xffff0000, v7
	ds_read_b128 v[4:7], v3
	v_pk_mul_f32 v[12:13], v[12:13], v[14:15]
	s_nop 0
	v_cvt_pk_bf16_f32 v3, v12, v13
	v_lshl_add_u64 v[12:13], v[30:31], 0, v[24:25]
	global_store_dwordx4 v[12:13], v[0:3], off sc1
	s_waitcnt lgkmcnt(0)
	s_nop 0
	v_lshlrev_b32_e32 v0, 16, v4
	v_and_b32_e32 v1, 0xffff0000, v4
	s_waitcnt vmcnt(3)
	v_lshlrev_b32_e32 v2, 16, v8
	v_and_b32_e32 v3, 0xffff0000, v8
	v_pk_mul_f32 v[0:1], v[0:1], v[2:3]
	v_lshlrev_b32_e32 v2, 16, v5
	v_and_b32_e32 v3, 0xffff0000, v5
	v_lshlrev_b32_e32 v4, 16, v9
	v_and_b32_e32 v5, 0xffff0000, v9
	v_pk_mul_f32 v[2:3], v[2:3], v[4:5]
	v_cvt_pk_bf16_f32 v0, v0, v1
	v_cvt_pk_bf16_f32 v1, v2, v3
	v_lshlrev_b32_e32 v2, 16, v6
	v_and_b32_e32 v3, 0xffff0000, v6
	v_lshlrev_b32_e32 v4, 16, v10
	v_and_b32_e32 v5, 0xffff0000, v10
	v_pk_mul_f32 v[2:3], v[2:3], v[4:5]
	v_lshlrev_b32_e32 v8, 16, v7
	v_cvt_pk_bf16_f32 v2, v2, v3
	v_lshl_add_u32 v3, v32, 7, v27
	v_and_b32_e32 v9, 0xffff0000, v7
	ds_read_b128 v[4:7], v3
	v_lshlrev_b32_e32 v10, 16, v11
	v_and_b32_e32 v11, 0xffff0000, v11
	v_pk_mul_f32 v[8:9], v[8:9], v[10:11]
	s_nop 0
	v_cvt_pk_bf16_f32 v3, v8, v9
	v_lshl_add_u64 v[8:9], v[30:31], 0, v[28:29]
	global_store_dwordx4 v[8:9], v[0:3], off sc1
	s_waitcnt lgkmcnt(0)
	s_nop 0
	v_lshlrev_b32_e32 v0, 16, v4
	v_and_b32_e32 v1, 0xffff0000, v4
	s_waitcnt vmcnt(3)
	v_lshlrev_b32_e32 v2, 16, v16
	v_and_b32_e32 v3, 0xffff0000, v16
	v_pk_mul_f32 v[0:1], v[0:1], v[2:3]
	v_lshlrev_b32_e32 v2, 16, v5
	v_and_b32_e32 v3, 0xffff0000, v5
	v_lshlrev_b32_e32 v4, 16, v17
	v_and_b32_e32 v5, 0xffff0000, v17
	v_pk_mul_f32 v[2:3], v[2:3], v[4:5]
	v_cvt_pk_bf16_f32 v0, v0, v1
	v_cvt_pk_bf16_f32 v1, v2, v3
	v_lshlrev_b32_e32 v2, 16, v6
	v_and_b32_e32 v3, 0xffff0000, v6
	v_lshlrev_b32_e32 v4, 16, v18
	v_and_b32_e32 v5, 0xffff0000, v18
	v_pk_mul_f32 v[2:3], v[2:3], v[4:5]
	v_lshlrev_b32_e32 v4, 16, v7
	v_and_b32_e32 v5, 0xffff0000, v7
	v_lshlrev_b32_e32 v6, 16, v19
	v_and_b32_e32 v7, 0xffff0000, v19
	v_pk_mul_f32 v[4:5], v[4:5], v[6:7]
	v_cvt_pk_bf16_f32 v2, v2, v3
	v_cvt_pk_bf16_f32 v3, v4, v5
	v_lshl_add_u64 v[4:5], v[30:31], 0, v[34:35]
	global_store_dwordx4 v[4:5], v[0:3], off sc1
	s_waitcnt lgkmcnt(0)
	s_barrier
	s_barrier
	s_cbranch_scc0 .LBB0_1017
	s_add_i32 s0, s90, -4
	s_lshr_b32 s98, s94, 7
	s_lshl_b32 s98, s98, 9
	s_lshl_b32 s99, s0, 7
	s_add_i32 s98, s98, s99
	s_and_b32 s99, s94, 0x7f
	s_add_i32 s0, s98, s99
	s_addk_i32 s0, 0x800
	s_ashr_i32 s1, s0, 31
	s_lshr_b32 s1, s1, 25
	s_add_i32 s1, s0, s1
	s_ashr_i32 s2, s1, 7
	s_and_b32 s1, s1, 0xffffff80
	s_sub_i32 s18, s0, s1
	s_mul_hi_i32 s0, s0, 0x2aaaaaab
	s_lshr_b32 s1, s0, 31
	s_ashr_i32 s0, s0, 8
	s_add_i32 s26, s0, s1
	s_mul_hi_i32 s0, s2, 0x2aaaaaab
	s_lshr_b32 s1, s0, 31
	s_lshr_b32 s0, s0, 1
	s_add_i32 s0, s0, s1
	s_mul_i32 s0, s0, 12
	s_ashr_i32 s27, s26, 31
	s_ashr_i32 s19, s18, 31
	s_lshl_b32 s4, s18, 6
	s_sub_i32 s24, s2, s0
	s_lshl_b64 s[0:1], s[26:27], 13
	s_lshl_b64 s[2:3], s[18:19], 6
	s_sub_i32 s19, 2, s4
	s_add_u32 s0, s0, s2
	s_addc_u32 s1, s1, s3
	s_add_u32 s34, s0, -3
	s_addc_u32 s35, s1, -1
	s_lshl_b32 s22, s24, 6
	s_ashr_i32 s23, s22, 31
	s_lshl_b64 s[0:1], s[22:23], 1
	s_add_u32 s0, s38, s0
	s_addc_u32 s1, s39, s1
	s_movk_i32 s4, 0x43
	v_lshl_add_u64 v[0:1], s[0:1], 0, v[124:125]
	v_cmp_gt_i32_e64 s[0:1], s4, v116
	v_cmp_lt_i32_e32 vcc, s19, v116
	s_and_b64 s[6:7], s[0:1], vcc
	v_mov_b32_e32 v65, v125
	v_mov_b32_e32 v66, v125
	v_mov_b32_e32 v67, v125
	s_and_saveexec_b64 s[2:3], s[6:7]
	s_cbranch_execz .LBB0_984
	v_lshl_add_u64 v[2:3], s[34:35], 0, v[116:117]
	s_movk_i32 s5, 0x600
	v_mad_u64_u32 v[4:5], s[6:7], v2, s5, v[0:1]
	v_mad_i32_i24 v5, v3, s5, v5
	global_load_dwordx4 v[64:67], v[4:5], off
	s_waitcnt vmcnt(0)
	v_mov_b32_e32 v125, v64

.LBB0_1018:
	s_mul_i32 s0, s90, s68
	s_lshr_b32 s98, s94, 6
	s_lshl_b32 s98, s98, 8
	s_lshl_b32 s99, s90, 6
	s_add_i32 s98, s98, s99
	s_and_b32 s99, s94, 63
	s_add_i32 s0, s98, s99
	s_bfe_i32 s3, s0, 0x1001e
	s_lshl_b32 s1, s0, 1
	s_ashr_i32 s2, s0, 31
	s_lshr_b32 s3, s3, 25
	s_lshr_b32 s2, s2, 26
	s_add_i32 s3, s1, s3
	s_add_i32 s2, s0, s2
	s_and_b32 s3, s3, 0xffffff80
	s_mul_hi_i32 s0, s0, 0x2aaaaaab
	s_ashr_i32 s2, s2, 6
	s_sub_i32 s18, s1, s3
	s_lshr_b32 s1, s0, 31
	s_ashr_i32 s0, s0, 7
	s_add_i32 s26, s0, s1
	s_mul_hi_i32 s0, s2, 0x2aaaaaab
	s_lshr_b32 s1, s0, 31
	s_lshr_b32 s0, s0, 1
	s_add_i32 s0, s0, s1
	s_mul_i32 s0, s0, 12
	s_ashr_i32 s27, s26, 31
	s_ashr_i32 s19, s18, 31
	s_lshl_b32 s4, s18, 6
	s_sub_i32 s34, s2, s0
	s_lshl_b64 s[0:1], s[26:27], 13
	s_lshl_b64 s[2:3], s[18:19], 6
	s_sub_i32 s35, 2, s4
	s_add_u32 s19, s0, -3
	s_addc_u32 s27, s1, -1
	s_add_u32 s36, s19, s2
	s_addc_u32 s37, s27, s3
	s_lshl_b32 s22, s34, 6
	s_ashr_i32 s23, s22, 31
	s_lshl_b64 s[0:1], s[22:23], 1
	s_add_u32 s0, s38, s0
	s_addc_u32 s1, s39, s1
	v_mov_b32_e32 v125, 0
	s_movk_i32 s4, 0x43
	v_lshl_add_u64 v[110:111], s[0:1], 0, v[124:125]
	v_cmp_gt_i32_e64 s[0:1], s4, v116
	v_cmp_lt_i32_e32 vcc, s35, v116
	s_and_b64 s[6:7], s[0:1], vcc
	v_mov_b32_e32 v64, 0
	v_mov_b32_e32 v65, 0
	v_mov_b32_e32 v66, 0
	v_mov_b32_e32 v67, 0
	s_and_saveexec_b64 s[2:3], s[6:7]
	s_cbranch_execz .LBB0_1020
	v_lshl_add_u64 v[0:1], s[36:37], 0, v[116:117]
	s_movk_i32 s5, 0x600
	v_mad_u64_u32 v[2:3], s[6:7], v0, s5, v[110:111]
	v_mad_i32_i24 v3, v1, s5, v3
	global_load_dwordx4 v[64:67], v[2:3], off

.LBB0_1163:
	s_cmp_lt_i32 s84, 8
	s_cselect_b64 s[0:1], -1, 0
	s_cmp_gt_i32 s85, 7
	s_cselect_b64 s[2:3], -1, 0
	s_and_b64 s[0:1], s[0:1], s[2:3]
	s_andn2_b64 vcc, exec, s[0:1]
	s_cbranch_vccnz .LBB0_1361
	s_mov_b64 s[52:53], s[82:83]
	s_add_u32 s67, s52, 0x3800000
	s_addc_u32 s68, s53, 0
	s_add_u32 s58, s52, 0x700000
	s_addc_u32 s59, s53, 0
	s_add_u32 s62, s52, 0xf9ff000
	s_addc_u32 s63, s53, 0
	s_add_u32 s60, s52, 0xf800000
	s_addc_u32 s61, s53, 0
	s_add_i32 s33, s70, 0
	v_mbcnt_lo_u32_b32 v182, -1, 0
	v_mbcnt_hi_u32_b32 v182, -1, v182
	s_mov_b64 s[0:1], -1
	s_cmpk_gt_u32 s91, 0xff
	v_lshlrev_b32_e32 v146, 4, v182
	v_ashrrev_i32_e32 v116, 3, v182
	s_cbranch_scc0 .LBB0_1223
	s_add_i32 s66, s90, -4
	v_readlane_b32 s0, v246, 27
	s_mul_i32 s0, s66, s0
	s_lshr_b32 s98, s94, 7
	s_lshl_b32 s98, s98, 9
	s_lshl_b32 s99, s66, 7
	s_add_i32 s98, s98, s99
	s_and_b32 s99, s94, 0x7f
	s_add_i32 s69, s98, s99
	s_addk_i32 s69, 0x800
	s_ashr_i32 s0, s69, 31
	s_lshr_b32 s0, s0, 25
	s_add_i32 s0, s69, s0
	s_ashr_i32 s71, s0, 7
	s_and_b32 s0, s0, 0xffffff80
	s_sub_i32 s18, s69, s0
	s_mul_hi_i32 s0, s69, 0x2aaaaaab
	s_lshr_b32 s1, s0, 31
	s_ashr_i32 s0, s0, 8
	s_add_i32 s20, s0, s1
	s_mul_hi_i32 s0, s71, 0x2aaaaaab
	s_lshr_b32 s1, s0, 31
	s_lshr_b32 s0, s0, 1
	s_add_i32 s0, s0, s1
	s_mul_i32 s0, s0, 12
	s_ashr_i32 s21, s20, 31
	s_ashr_i32 s19, s18, 31
	s_lshl_b32 s2, s18, 6
	s_sub_i32 s64, s71, s0
	s_lshl_b64 s[54:55], s[20:21], 13
	s_lshl_b64 s[0:1], s[18:19], 6
	s_sub_i32 s19, 2, s2
	s_add_u32 s0, s54, s0
	s_addc_u32 s1, s55, s1
	s_add_u32 s24, s0, -3
	s_addc_u32 s25, s1, -1
	s_lshl_b32 s22, s64, 6
	s_ashr_i32 s23, s22, 31
	s_lshl_b64 s[56:57], s[22:23], 1
	s_add_u32 s0, s67, s56
	s_addc_u32 s1, s68, s57
	v_and_b32_e32 v100, 0x70, v146
	v_mov_b32_e32 v101, 0
	s_movk_i32 s4, 0x43
	v_lshl_add_u64 v[0:1], s[0:1], 0, v[100:101]
	v_cmp_gt_i32_e64 s[0:1], s4, v116
	v_cmp_lt_i32_e32 vcc, s19, v116
	s_and_b64 s[6:7], s[0:1], vcc
	v_ashrrev_i32_e32 v117, 31, v116
	v_mov_b32_e32 v64, 0
	v_mov_b32_e32 v65, 0
	v_mov_b32_e32 v66, 0
	v_mov_b32_e32 v67, 0
	s_and_saveexec_b64 s[2:3], s[6:7]
	s_cbranch_execz .LBB0_1167
	v_lshl_add_u64 v[2:3], s[24:25], 0, v[116:117]
	s_movk_i32 s5, 0x600
	v_mad_u64_u32 v[4:5], s[6:7], v2, s5, v[0:1]
	v_mad_i32_i24 v5, v3, s5, v5
	global_load_dwordx4 v[64:67], v[4:5], off

.LBB0_1223:
	s_and_b64 vcc, exec, s[0:1]
	s_cbranch_vccz .LBB0_1297
	v_readlane_b32 s0, v246, 27
	s_mul_i32 s0, s90, s0
	s_lshr_b32 s98, s94, 6
	s_lshl_b32 s98, s98, 8
	s_lshl_b32 s99, s90, 6
	s_add_i32 s98, s98, s99
	s_and_b32 s99, s94, 63
	s_add_i32 s0, s98, s99
	s_bfe_i32 s3, s0, 0x1001e
	s_lshl_b32 s1, s0, 1
	s_ashr_i32 s2, s0, 31
	s_lshr_b32 s3, s3, 25
	s_lshr_b32 s2, s2, 26
	s_add_i32 s3, s1, s3
	s_add_i32 s2, s0, s2
	s_and_b32 s3, s3, 0xffffff80
	s_mul_hi_i32 s0, s0, 0x2aaaaaab
	s_ashr_i32 s2, s2, 6
	s_sub_i32 s56, s1, s3
	s_lshr_b32 s1, s0, 31
	s_ashr_i32 s0, s0, 7
	s_add_i32 s64, s0, s1
	s_mul_hi_i32 s0, s2, 0x2aaaaaab
	s_lshr_b32 s1, s0, 31
	s_lshr_b32 s0, s0, 1
	s_add_i32 s0, s0, s1
	s_mul_i32 s0, s0, 12
	s_ashr_i32 s65, s64, 31
	s_ashr_i32 s57, s56, 31
	s_lshl_b32 s72, s56, 6
	s_sub_i32 s66, s2, s0
	s_lshl_b64 s[0:1], s[64:65], 13
	s_lshl_b64 s[2:3], s[56:57], 6
	s_sub_i32 s22, 2, s72
	s_add_u32 s57, s0, -3
	s_addc_u32 s71, s1, -1
	s_add_u32 s8, s57, s2
	s_addc_u32 s9, s71, s3
	s_lshl_b32 s6, s66, 6
	s_ashr_i32 s7, s6, 31
	s_lshl_b64 s[54:55], s[6:7], 1
	s_add_u32 s0, s67, s54
	s_addc_u32 s1, s68, s55
	v_and_b32_e32 v136, 0x70, v146
	v_mov_b32_e32 v137, 0
	s_movk_i32 s4, 0x43
	v_lshl_add_u64 v[106:107], s[0:1], 0, v[136:137]
	v_cmp_gt_i32_e64 s[0:1], s4, v116
	v_cmp_lt_i32_e32 vcc, s22, v116
	s_and_b64 s[10:11], s[0:1], vcc
	v_ashrrev_i32_e32 v117, 31, v116
	v_mov_b32_e32 v64, 0
	v_mov_b32_e32 v65, 0
	v_mov_b32_e32 v66, 0
	v_mov_b32_e32 v67, 0
	s_and_saveexec_b64 s[2:3], s[10:11]
	s_cbranch_execz .LBB0_1226
	v_lshl_add_u64 v[0:1], s[8:9], 0, v[116:117]
	s_movk_i32 s5, 0x600
	v_mad_u64_u32 v[2:3], s[10:11], v0, s5, v[106:107]
	v_mad_i32_i24 v3, v1, s5, v3
	global_load_dwordx4 v[64:67], v[2:3], off
